# v55 + tile raster WGM 8->4 in P2 and P7 (XCD round covers 4 token tiles x 8 column tiles)
# speedup vs baseline: 1.0113x; 1.0080x over previous
;     __host__ __device__ bool next(int i, Unit& u) const {
;         const long L = (long)i * G + c; if (L >= nwg) return false;
;         int wgid = (int)L; { const int q = nwg / NXCD, r = nwg % NXCD, xcd = wgid % NXCD, off = wgid / NXCD; wgid = (xcd < r ? xcd * (q + 1) : r * (q + 1) + (xcd - r) * q) + off; }
;         const int nig = WGM * nN, gid = wgid / nig, fm = gid * WGM, gsz = (nM - fm) < WGM ? (nM - fm) : WGM;
;         u.pm = fm + ((wgid % nig) % gsz); u.pn = (wgid % nig) / gsz; return true;
; template <class Epi, class Sched, bool ALIGN_EPI = false, bool SP2 = false>
; __device__ __forceinline__ void gemm_phase(PG8_LAS unsigned char* lds, const Gemm g, const Sched& S, const Epi& E) {
;     ...
;     for (int i = 0; i < 2; ++i) { int R, C; stage_rc(tid * 16 + i * 8192, R, C); const int Rb = Epi::PERM ? ((R & ~31) + perm32(R & 31)) : R;
;         voffA[i] = (unsigned)(R * g.lda + C) * 2u; voffB[i] = (unsigned)(Rb * g.ldb + C) * 2u; }
;     const size_t kstep = (size_t)(BK * 2);
;     const size_t hstepA = (size_t)HALF * g.lda * 2, hstepB = (size_t)HALF * g.ldb * 2;
;     const size_t tstepA = 2 * hstepA, tstepB = 2 * hstepB, apn = (size_t)g.apn;
;     const unsigned ldsw = (unsigned)wid * 1024u;
;     const int aoff = lds_byte(wr * 64 + fr, fq * 8), boff = lds_byte(wc * 32 + fr, fq * 8);
;     ...
;     Unit cur, nxt; int ui = 0;
;     if (!S.next(0, cur)) return;
;     f32x4 acc[2][2][4][2];
; #pragma unroll
;     for (int a = 0; a < 2; ++a)
; #pragma unroll
;         for (int b = 0; b < 2; ++b)
; #pragma unroll
;             for (int m = 0; m < 4; ++m)
; #pragma unroll
;                 for (int n = 0; n < 2; ++n) acc[a][b][m][n] = (f32x4){0.f, 0.f, 0.f, 0.f};
;     bf16x8 At[4][2], B0[2][2], B1[2][2];
;     const char* cA = (const char*)g.A + (size_t)cur.pm * tstepA + (size_t)cur.pn * apn; const char* cB = (const char*)g.Bt + (size_t)cur.pn * tstepB;
;     S.a_ready(cur);
;     if constexpr (SP2) {
;         PG8_STAGE(PG8_SB(0, 0), cB, voffB); PG8_STAGE(PG8_SB(0, 1), cB + hstepB, voffB); PG8_STAGE(PG8_SA(0, 0), cA, voffA); PG8_STAGE(PG8_SA(0, 1), cA + hstepA, voffA);
;         if (wr == 1) PG8_BAR;
;         PG8_WAIT_V(2); PG8_BAR;
;         PG8_STAGE(PG8_SB(1, 0), cB + kstep, voffB); PG8_STAGE(PG8_SA(1, 0), cA + kstep, voffA); PG8_STAGE(PG8_SB(1, 1), cB + hstepB + kstep, voffB);
;         PG8_WAIT_V(6); PG8_BAR;
;     } else {
.LBB0_188:
	s_or_b64 exec, exec, s[0:1]
	s_add_u32 s24, s68, 0x5000000
	s_addc_u32 s25, s69, 0
	s_add_u32 s18, s68, 0x11000000
	s_addc_u32 s19, s69, 0
	s_add_u32 s42, s68, 0x19000000
	s_addc_u32 s43, s69, 0
	s_add_u32 s44, s68, 0x21000000
	s_addc_u32 s45, s69, 0
	s_add_u32 s0, s68, 0x29000000
	s_addc_u32 s1, s69, 0
	s_add_u32 s20, s68, 0x2d000000
	s_addc_u32 s21, s69, 0
	s_add_u32 s30, s68, 0x2000
	s_addc_u32 s31, s69, 0
	s_cmpk_lt_i32 s26, 0x1600
	s_waitcnt lgkmcnt(0)
	v_mov_b32_e32 v0, v174
	v_mov_b32_e32 v9, v174
	s_cselect_b64 s[2:3], -1, 0
	s_barrier
	v_writelane_b32 v238, s2, 16
	s_cmpk_gt_i32 s26, 0x15ff
	v_readfirstlane_b32 s4, v9
	v_writelane_b32 v238, s3, 17
	s_cbranch_scc1 .LBB0_227
	v_lshlrev_b32_e32 v0, 4, v9
	v_add_u32_e32 v1, 0x2000, v0
	v_ashrrev_i32_e32 v2, 31, v1
	v_lshrrev_b32_e32 v2, 22, v2
	v_add_u32_e32 v2, v1, v2
	v_ashrrev_i32_e32 v8, 10, v2
	v_mul_i32_i24_e32 v2, 0x400, v8
	v_sub_u32_e32 v1, v1, v2
	v_lshrrev_b32_e32 v2, 4, v1
	v_bitop3_b32 v1, v2, v1, 32 bitop3:0x6c
	v_ashrrev_i32_e32 v2, 31, v1
	v_lshrrev_b32_e32 v2, 26, v2
	v_add_u32_e32 v2, v1, v2
	v_lshlrev_b32_e32 v3, 3, v8
	v_ashrrev_i32_e32 v10, 6, v2
	v_and_b32_e32 v3, -16, v3
	v_add_u32_e32 v3, v10, v3
	v_and_b32_e32 v4, 3, v10
	s_mov_b32 s2, 0x1fffe0
	v_lshrrev_b32_e32 v5, 2, v3
	v_lshlrev_b32_e32 v6, 1, v3
	v_and_b32_e32 v2, 0xc0, v2
	v_and_or_b32 v4, v3, s2, v4
	v_and_b32_e32 v5, 4, v5
	v_and_b32_e32 v6, 24, v6
	v_sub_u32_e32 v1, v1, v2
	v_mov_b32_e32 v2, 1
	v_or3_b32 v4, v4, v5, v6
	v_lshlrev_b32_e32 v5, 5, v8
	v_ashrrev_i16_sdwa v1, v2, sext(v1) dst_sel:DWORD dst_unused:UNUSED_PAD src0_sel:DWORD src1_sel:BYTE_0
	v_and_b32_e32 v5, 32, v5
	v_bfe_i32 v11, v1, 0, 16
	v_add_lshl_u32 v1, v5, v11, 1
	v_lshl_add_u32 v128, v4, 11, v1
	v_lshl_add_u32 v130, v3, 11, v1
	v_bfe_i32 v1, v9, 27, 1
	v_lshrrev_b32_e32 v1, 22, v1
	v_add_u32_e32 v1, v0, v1
	v_and_b32_e32 v1, 0xfffffc00, v1
	v_sub_u32_e32 v0, v0, v1
	v_lshrrev_b32_e32 v1, 4, v0
	v_ashrrev_i32_e32 v3, 31, v9
	v_bitop3_b32 v0, v1, v0, 32 bitop3:0x6c
	v_lshrrev_b32_e32 v3, 26, v3
	v_ashrrev_i32_e32 v1, 31, v0
	v_add_u32_e32 v3, v9, v3
	v_lshrrev_b32_e32 v1, 26, v1
	v_ashrrev_i32_e32 v13, 6, v3
	v_add_u32_e32 v1, v0, v1
	v_lshlrev_b32_e32 v3, 3, v13
	v_ashrrev_i32_e32 v12, 6, v1
	v_and_b32_e32 v3, -16, v3
	v_add_u32_e32 v3, v12, v3
	v_and_b32_e32 v4, 3, v12
	s_ashr_i32 s35, s26, 31
	v_and_or_b32 v4, v3, s2, v4
	s_lshr_b32 s2, s35, 29
	s_add_i32 s2, s26, s2
	s_ashr_i32 s5, s4, 6
	s_ashr_i32 s6, s2, 3
	s_and_b32 s2, s2, -8
	s_ashr_i32 s3, s4, 8
	s_lshl_b32 s27, s5, 10
	s_sub_i32 s2, s26, s2
	s_cmp_lt_i32 s2, 0
	s_movk_i32 s41, 0x2c1
	s_cselect_b32 s7, s41, 0x2c0
	s_mul_i32 s2, s2, s7
	s_add_i32 s2, s2, s6
	s_mul_hi_i32 s6, s2, 0x2e8ba2e9
	s_lshr_b32 s7, s6, 31
	s_ashr_i32 s6, s6, 4
	s_add_i32 s6, s6, s7
	s_lshl_b32 s7, s6, 2
	s_mulk_i32 s6, 0x58
	s_sub_i32 s6, s2, s6
	s_bfe_u32 s2, s6, 0x2001e
	s_add_i32 s8, s6, s2
	s_sext_i32_i16 s2, s8
	s_and_b32 s8, s8, 0xfffc
	s_sub_i32 s6, s6, s8
	s_sext_i32_i16 s6, s6
	v_lshrrev_b32_e32 v5, 2, v3
	v_lshlrev_b32_e32 v6, 1, v3
	v_and_b32_e32 v1, 0xc0, v1
	s_lshr_b32 s2, s2, 2
	s_add_i32 s58, s7, s6
	v_and_b32_e32 v5, 4, v5
	v_and_b32_e32 v6, 24, v6
	v_sub_u32_e32 v0, v0, v1
	s_ashr_i32 s59, s58, 31
	s_bfe_i64 s[8:9], s[2:3], 0x100000
	v_or3_b32 v4, v4, v5, v6
	v_lshlrev_b32_e32 v5, 5, v13
	v_ashrrev_i16_sdwa v0, v2, sext(v0) dst_sel:DWORD dst_unused:UNUSED_PAD src0_sel:DWORD src1_sel:BYTE_0
	s_lshl_b64 s[6:7], s[58:59], 19
	s_lshl_b64 s[8:9], s[8:9], 19
	v_and_b32_e32 v5, 32, v5
	v_bfe_i32 v14, v0, 0, 16
	s_add_u32 s66, s82, s8
	v_add_lshl_u32 v0, v5, v14, 1
	s_addc_u32 s67, s83, s9
	s_add_i32 s59, s27, 0
	v_lshl_add_u32 v132, v4, 11, v0
	s_add_i32 m0, s59, 0x10000
	v_lshl_add_u32 v134, v3, 11, v0
	global_load_lds_dwordx4 v132, s[66:67]
	s_add_i32 m0, s59, 0x12000
	s_add_u32 s8, s66, 0x40000
	global_load_lds_dwordx4 v128, s[66:67]
	s_addc_u32 s9, s67, 0
	s_add_i32 m0, s59, 0x14000
	v_writelane_b32 v238, s97, 18
	global_load_lds_dwordx4 v132, s[8:9]
	s_add_i32 m0, s59, 0x16000
	s_add_u32 s60, s24, s6
	s_addc_u32 s61, s25, s7
	s_add_i32 s86, s59, 0x2000
	global_load_lds_dwordx4 v128, s[8:9]
	s_mov_b32 m0, s59
	s_add_u32 s6, s60, 0x40000
	global_load_lds_dwordx4 v134, s[60:61]
	s_mov_b32 m0, s86
	s_addc_u32 s7, s61, 0
	s_add_i32 s87, s59, 0x4000
	global_load_lds_dwordx4 v130, s[60:61]
	s_mov_b32 m0, s87
	s_add_i32 s88, s59, 0x6000
	global_load_lds_dwordx4 v134, s[6:7]
	s_mov_b32 m0, s88
	v_mov_b32_e32 v137, 0
	global_load_lds_dwordx4 v130, s[6:7]
	v_writelane_b32 v238, s96, 19
	v_mov_b32_e32 v133, v137
	v_mov_b32_e32 v129, v137
	v_mov_b32_e32 v135, v137
	v_mov_b32_e32 v131, v137
	s_cmp_eq_u32 s3, 1
	v_writelane_b32 v238, s94, 20
	s_movk_i32 s89, 0x2000
	s_mov_b32 s90, 0
	v_lshl_add_u64 v[6:7], s[66:67], 0, v[132:133]
	v_lshl_add_u64 v[4:5], s[66:67], 0, v[128:129]
	v_lshl_add_u64 v[0:1], s[60:61], 0, v[134:135]
	s_cselect_b64 s[6:7], -1, 0
	s_cmp_lg_u32 s3, 1
	v_lshl_add_u64 v[2:3], s[60:61], 0, v[130:131]
	v_writelane_b32 v238, s95, 21
	s_cbranch_scc1 .LBB0_191
	s_barrier

;     __host__ __device__ bool next(int i, Unit& u) const {
;         const long L = (long)i * G + c; if (L >= nwg) return false;
;         int wgid = (int)L; { const int q = nwg / NXCD, r = nwg % NXCD, xcd = wgid % NXCD, off = wgid / NXCD; wgid = (xcd < r ? xcd * (q + 1) : r * (q + 1) + (xcd - r) * q) + off; }
;         const int nig = WGM * nN, gid = wgid / nig, fm = gid * WGM, gsz = (nM - fm) < WGM ? (nM - fm) : WGM;
;         u.pm = fm + ((wgid % nig) % gsz); u.pn = (wgid % nig) / gsz; return true;
; template <class Epi, class Sched, bool ALIGN_EPI = false, bool SP2 = false>
; __device__ __forceinline__ void gemm_phase(PG8_LAS unsigned char* lds, const Gemm g, const Sched& S, const Epi& E) {
;     ...
;         const bool has_next = S.next(ui + 1, nxt);
;         const char* nA = has_next ? (const char*)g.A + (size_t)nxt.pm * tstepA + (size_t)nxt.pn * apn : cA; const char* nB = has_next ? (const char*)g.Bt + (size_t)nxt.pn * tstepB : cB;
.LBB0_194:
	s_add_i32 s90, s90, 1
	s_mul_i32 s4, s90, s94
	s_mul_hi_u32 s5, s90, s95
	s_add_i32 s5, s5, s4
	s_mul_i32 s4, s90, s95
	s_add_u32 s16, s4, s26
	s_addc_u32 s17, s5, s35
	v_cmp_gt_i64_e32 vcc, s[16:17], v[144:145]
	v_cmp_lt_i64_e64 s[4:5], s[16:17], v[142:143]
	s_cbranch_vccnz .LBB0_196
	s_ashr_i32 s12, s16, 31
	s_lshr_b32 s12, s12, 29
	s_add_i32 s12, s16, s12
	s_ashr_i32 s13, s12, 3
	s_and_b32 s12, s12, -8
	s_sub_i32 s12, s16, s12
	s_cmp_lt_i32 s12, 0
	s_cselect_b32 s14, s41, 0x2c0
	s_mul_i32 s12, s12, s14
	s_add_i32 s12, s12, s13
	s_mul_hi_i32 s13, s12, 0x2e8ba2e9
	s_lshr_b32 s14, s13, 31
	s_ashr_i32 s13, s13, 4
	s_add_i32 s13, s13, s14
	s_lshl_b32 s14, s13, 2
	s_sub_i32 s15, 0x100, s14
	s_min_i32 s15, s15, 4
	s_abs_i32 s16, s15
	v_cvt_f32_u32_e32 v0, s16
	s_sub_i32 s56, 0, s16
	s_mulk_i32 s13, 0x58
	s_sub_i32 s13, s12, s13
	v_rcp_iflag_f32_e32 v0, v0
	s_abs_i32 s12, s13
	s_xor_b32 s17, s13, s15
	s_ashr_i32 s17, s17, 31
	v_mul_f32_e32 v0, 0x4f7ffffe, v0
	v_cvt_u32_f32_e32 v0, v0
	s_nop 0
	v_readfirstlane_b32 s57, v0
	s_mul_i32 s56, s56, s57
	s_mul_hi_u32 s56, s57, s56
	s_add_i32 s57, s57, s56
	s_mul_hi_u32 s56, s12, s57
	s_mul_i32 s57, s56, s16
	s_sub_i32 s12, s12, s57
	s_add_i32 s74, s56, 1
	s_sub_i32 s57, s12, s16
	s_cmp_ge_u32 s12, s16
	s_cselect_b32 s56, s74, s56
	s_cselect_b32 s12, s57, s12
	s_add_i32 s57, s56, 1
	s_cmp_ge_u32 s12, s16
	s_cselect_b32 s12, s57, s56
	s_xor_b32 s12, s12, s17
	s_sub_i32 s12, s12, s17
	s_mul_i32 s15, s12, s15
	s_sub_i32 s13, s13, s15
	s_add_i32 s14, s14, s13

;     __host__ __device__ bool next(int i, Unit& u) const {
;         const long L = (long)i * G + c; if (L >= nwg) return false;
;         int wgid = (int)L; { const int q = nwg / NXCD, r = nwg % NXCD, xcd = wgid % NXCD, off = wgid / NXCD; wgid = (xcd < r ? xcd * (q + 1) : r * (q + 1) + (xcd - r) * q) + off; }
;         const int nig = WGM * nN, gid = wgid / nig, fm = gid * WGM, gsz = (nM - fm) < WGM ? (nM - fm) : WGM;
;         u.pm = fm + ((wgid % nig) % gsz); u.pn = (wgid % nig) / gsz; return true;
; template <class Epi, class Sched, bool ALIGN_EPI = false, bool SP2 = false>
; __device__ __forceinline__ void gemm_phase(PG8_LAS unsigned char* lds, const Gemm g, const Sched& S, const Epi& E) {
;     ...
;     for (int i = 0; i < 2; ++i) { int R, C; stage_rc(tid * 16 + i * 8192, R, C); const int Rb = Epi::PERM ? ((R & ~31) + perm32(R & 31)) : R;
;         voffA[i] = (unsigned)(R * g.lda + C) * 2u; voffB[i] = (unsigned)(Rb * g.ldb + C) * 2u; }
;     const size_t kstep = (size_t)(BK * 2);
;     const size_t hstepA = (size_t)HALF * g.lda * 2, hstepB = (size_t)HALF * g.ldb * 2;
;     const size_t tstepA = 2 * hstepA, tstepB = 2 * hstepB, apn = (size_t)g.apn;
;     const unsigned ldsw = (unsigned)wid * 1024u;
;     const int aoff = lds_byte(wr * 64 + fr, fq * 8), boff = lds_byte(wc * 32 + fr, fq * 8);
;     ...
;     Unit cur, nxt; int ui = 0;
;     if (!S.next(0, cur)) return;
;     f32x4 acc[2][2][4][2];
; #pragma unroll
;     for (int a = 0; a < 2; ++a)
; #pragma unroll
;         for (int b = 0; b < 2; ++b)
; #pragma unroll
;             for (int m = 0; m < 4; ++m)
; #pragma unroll
;                 for (int n = 0; n < 2; ++n) acc[a][b][m][n] = (f32x4){0.f, 0.f, 0.f, 0.f};
;     bf16x8 At[4][2], B0[2][2], B1[2][2];
;     const char* cA = (const char*)g.A + (size_t)cur.pm * tstepA + (size_t)cur.pn * apn; const char* cB = (const char*)g.Bt + (size_t)cur.pn * tstepB;
;     S.a_ready(cur);
;     if constexpr (SP2) {
;         PG8_STAGE(PG8_SB(0, 0), cB, voffB); PG8_STAGE(PG8_SB(0, 1), cB + hstepB, voffB); PG8_STAGE(PG8_SA(0, 0), cA, voffA); PG8_STAGE(PG8_SA(0, 1), cA + hstepA, voffA);
;         if (wr == 1) PG8_BAR;
;         PG8_WAIT_V(2); PG8_BAR;
;         PG8_STAGE(PG8_SB(1, 0), cB + kstep, voffB); PG8_STAGE(PG8_SA(1, 0), cA + kstep, voffA); PG8_STAGE(PG8_SB(1, 1), cB + hstepB + kstep, voffB);
;         PG8_WAIT_V(6); PG8_BAR;
;     } else {
.LBB0_596:
	s_or_b64 exec, exec, s[0:1]
	v_readlane_b32 s0, v238, 16
	s_waitcnt lgkmcnt(0)
	v_mov_b32_e32 v0, v174
	v_mov_b32_e32 v9, v174
	v_readlane_b32 s1, v238, 17
	s_barrier
	s_andn2_b64 vcc, exec, s[0:1]
	v_readfirstlane_b32 s3, v9
	s_cbranch_vccnz .LBB0_612
	v_lshlrev_b32_e32 v0, 4, v9
	v_add_u32_e32 v1, 0x2000, v0
	v_ashrrev_i32_e32 v2, 31, v1
	v_lshrrev_b32_e32 v2, 22, v2
	v_add_u32_e32 v2, v1, v2
	v_ashrrev_i32_e32 v8, 10, v2
	v_mul_i32_i24_e32 v2, 0x400, v8
	v_sub_u32_e32 v1, v1, v2
	v_lshrrev_b32_e32 v2, 4, v1
	v_bitop3_b32 v1, v2, v1, 32 bitop3:0x6c
	v_ashrrev_i32_e32 v2, 31, v1
	v_lshrrev_b32_e32 v2, 26, v2
	v_add_u32_e32 v2, v1, v2
	v_lshlrev_b32_e32 v3, 3, v8
	v_ashrrev_i32_e32 v10, 6, v2
	v_and_b32_e32 v3, -16, v3
	v_add_u32_e32 v3, v10, v3
	v_and_b32_e32 v4, 3, v10
	s_mov_b32 s0, 0x1fffe0
	v_lshrrev_b32_e32 v5, 2, v3
	v_lshlrev_b32_e32 v6, 1, v3
	v_and_b32_e32 v2, 0xc0, v2
	v_and_or_b32 v4, v3, s0, v4
	v_and_b32_e32 v5, 4, v5
	v_and_b32_e32 v6, 24, v6
	v_sub_u32_e32 v1, v1, v2
	v_mov_b32_e32 v2, 1
	v_or3_b32 v4, v4, v5, v6
	v_lshlrev_b32_e32 v5, 5, v8
	v_ashrrev_i16_sdwa v1, v2, sext(v1) dst_sel:DWORD dst_unused:UNUSED_PAD src0_sel:DWORD src1_sel:BYTE_0
	v_and_b32_e32 v5, 32, v5
	v_bfe_i32 v11, v1, 0, 16
	v_add_lshl_u32 v1, v5, v11, 1
	v_lshl_add_u32 v128, v4, 11, v1
	v_lshl_add_u32 v130, v3, 11, v1
	v_bfe_i32 v1, v9, 27, 1
	v_lshrrev_b32_e32 v1, 22, v1
	v_add_u32_e32 v1, v0, v1
	v_and_b32_e32 v1, 0xfffffc00, v1
	v_sub_u32_e32 v0, v0, v1
	v_lshrrev_b32_e32 v1, 4, v0
	v_ashrrev_i32_e32 v3, 31, v9
	v_bitop3_b32 v0, v1, v0, 32 bitop3:0x6c
	v_lshrrev_b32_e32 v3, 26, v3
	v_ashrrev_i32_e32 v1, 31, v0
	v_add_u32_e32 v3, v9, v3
	v_lshrrev_b32_e32 v1, 26, v1
	v_ashrrev_i32_e32 v13, 6, v3
	v_add_u32_e32 v1, v0, v1
	v_lshlrev_b32_e32 v3, 3, v13
	v_ashrrev_i32_e32 v12, 6, v1
	v_and_b32_e32 v3, -16, v3
	v_add_u32_e32 v3, v12, v3
	v_and_b32_e32 v4, 3, v12
	s_ashr_i32 s23, s26, 31
	v_and_or_b32 v4, v3, s0, v4
	s_lshr_b32 s0, s23, 29
	s_add_i32 s0, s26, s0
	s_ashr_i32 s6, s3, 6
	s_ashr_i32 s1, s0, 3
	s_and_b32 s0, s0, -8
	s_ashr_i32 s8, s3, 8
	s_lshl_b32 s22, s6, 10
	s_sub_i32 s0, s26, s0
	s_cmp_lt_i32 s0, 0
	s_movk_i32 s28, 0x2c1
	s_cselect_b32 s2, s28, 0x2c0
	s_mul_i32 s0, s0, s2
	s_add_i32 s0, s0, s1
	s_mul_hi_i32 s1, s0, 0x2e8ba2e9
	s_lshr_b32 s2, s1, 31
	s_ashr_i32 s1, s1, 4
	s_add_i32 s1, s1, s2
	s_lshl_b32 s7, s1, 2
	s_mulk_i32 s1, 0x58
	s_sub_i32 s0, s0, s1
	s_bfe_u32 s1, s0, 0x2001e
	s_add_i32 s1, s0, s1
	s_sext_i32_i16 s2, s1
	s_and_b32 s1, s1, 0xfffc
	s_sub_i32 s0, s0, s1
	s_sext_i32_i16 s0, s0
	v_lshrrev_b32_e32 v5, 2, v3
	v_lshlrev_b32_e32 v6, 1, v3
	v_and_b32_e32 v1, 0xc0, v1
	s_lshr_b32 s2, s2, 2
	s_add_i32 s36, s7, s0
	v_and_b32_e32 v5, 4, v5
	v_and_b32_e32 v6, 24, v6
	v_sub_u32_e32 v0, v0, v1
	s_ashr_i32 s37, s36, 31
	s_bfe_i64 s[10:11], s[2:3], 0x100000
	v_or3_b32 v4, v4, v5, v6
	v_lshlrev_b32_e32 v5, 5, v13
	v_ashrrev_i16_sdwa v0, v2, sext(v0) dst_sel:DWORD dst_unused:UNUSED_PAD src0_sel:DWORD src1_sel:BYTE_0
	s_lshl_b64 s[0:1], s[36:37], 19
	s_lshl_b64 s[10:11], s[10:11], 19
	v_and_b32_e32 v5, 32, v5
	v_bfe_i32 v14, v0, 0, 16
	s_add_u32 s40, s60, s10
	v_add_lshl_u32 v0, v5, v14, 1
	s_addc_u32 s41, s61, s11
	s_add_i32 s29, s22, 0
	v_lshl_add_u32 v132, v4, 11, v0
	s_add_i32 m0, s29, 0x10000
	v_lshl_add_u32 v134, v3, 11, v0
	global_load_lds_dwordx4 v132, s[40:41]
	s_add_i32 m0, s29, 0x12000
	s_add_u32 s10, s40, 0x40000
	global_load_lds_dwordx4 v128, s[40:41]
	s_addc_u32 s11, s41, 0
	s_add_i32 m0, s29, 0x14000
	v_mov_b32_e32 v133, 0
	global_load_lds_dwordx4 v132, s[10:11]
	s_add_i32 m0, s29, 0x16000
	s_add_u32 s38, s24, s0
	s_addc_u32 s39, s25, s1
	s_add_i32 s30, s29, 0x2000
	global_load_lds_dwordx4 v128, s[10:11]
	s_mov_b32 m0, s29
	s_add_u32 s0, s38, 0x40000
	global_load_lds_dwordx4 v134, s[38:39]
	s_mov_b32 m0, s30
	s_addc_u32 s1, s39, 0
	s_add_i32 s31, s29, 0x4000
	global_load_lds_dwordx4 v130, s[38:39]
	s_mov_b32 m0, s31
	s_add_i32 s35, s29, 0x6000
	global_load_lds_dwordx4 v134, s[0:1]
	s_mov_b32 m0, s35
	v_mov_b32_e32 v129, v133
	global_load_lds_dwordx4 v130, s[0:1]
	v_mov_b32_e32 v135, v133
	v_mov_b32_e32 v131, v133
	s_cmp_eq_u32 s8, 1
	s_mov_b32 s37, 0
	v_lshl_add_u64 v[6:7], s[40:41], 0, v[132:133]
	v_lshl_add_u64 v[4:5], s[40:41], 0, v[128:129]
	v_lshl_add_u64 v[0:1], s[38:39], 0, v[134:135]
	s_cselect_b64 s[0:1], -1, 0
	s_cmp_lg_u32 s8, 1
	v_lshl_add_u64 v[2:3], s[38:39], 0, v[130:131]
	s_cbranch_scc1 .LBB0_599
	s_barrier

;     __host__ __device__ bool next(int i, Unit& u) const {
;         const long L = (long)i * G + c; if (L >= nwg) return false;
;         int wgid = (int)L; { const int q = nwg / NXCD, r = nwg % NXCD, xcd = wgid % NXCD, off = wgid / NXCD; wgid = (xcd < r ? xcd * (q + 1) : r * (q + 1) + (xcd - r) * q) + off; }
;         const int nig = WGM * nN, gid = wgid / nig, fm = gid * WGM, gsz = (nM - fm) < WGM ? (nM - fm) : WGM;
;         u.pm = fm + ((wgid % nig) % gsz); u.pn = (wgid % nig) / gsz; return true;
; template <class Epi, class Sched, bool ALIGN_EPI = false, bool SP2 = false>
; __device__ __forceinline__ void gemm_phase(PG8_LAS unsigned char* lds, const Gemm g, const Sched& S, const Epi& E) {
;     ...
;         const bool has_next = S.next(ui + 1, nxt);
;         const char* nA = has_next ? (const char*)g.A + (size_t)nxt.pm * tstepA + (size_t)nxt.pn * apn : cA; const char* nB = has_next ? (const char*)g.Bt + (size_t)nxt.pn * tstepB : cB;
.LBB0_602:
	s_add_i32 s37, s37, 1
	s_mul_i32 s2, s37, s46
	s_mul_hi_u32 s3, s37, s47
	s_add_i32 s3, s3, s2
	s_mul_i32 s2, s37, s47
	s_add_u32 s14, s2, s26
	s_addc_u32 s15, s3, s23
	v_cmp_gt_i64_e32 vcc, s[14:15], v[142:143]
	v_cmp_lt_i64_e64 s[2:3], s[14:15], v[140:141]
	s_cbranch_vccnz .LBB0_604
	s_ashr_i32 s10, s14, 31
	s_lshr_b32 s10, s10, 29
	s_add_i32 s10, s14, s10
	s_ashr_i32 s11, s10, 3
	s_and_b32 s10, s10, -8
	s_sub_i32 s10, s14, s10
	s_cmp_lt_i32 s10, 0
	s_cselect_b32 s12, s28, 0x2c0
	s_mul_i32 s10, s10, s12
	s_add_i32 s10, s10, s11
	s_mul_hi_i32 s11, s10, 0x2e8ba2e9
	s_lshr_b32 s12, s11, 31
	s_ashr_i32 s11, s11, 4
	s_add_i32 s11, s11, s12
	s_lshl_b32 s12, s11, 2
	s_sub_i32 s13, 0x100, s12
	s_min_i32 s13, s13, 4
	s_abs_i32 s14, s13
	v_cvt_f32_u32_e32 v0, s14
	s_sub_i32 s16, 0, s14
	s_mulk_i32 s11, 0x58
	s_sub_i32 s11, s10, s11
	v_rcp_iflag_f32_e32 v0, v0
	s_abs_i32 s10, s11
	s_xor_b32 s15, s11, s13
	s_ashr_i32 s15, s15, 31
	v_mul_f32_e32 v0, 0x4f7ffffe, v0
	v_cvt_u32_f32_e32 v0, v0
	s_nop 0
	v_readfirstlane_b32 s17, v0
	s_mul_i32 s16, s16, s17
	s_mul_hi_u32 s16, s17, s16
	s_add_i32 s17, s17, s16
	s_mul_hi_u32 s16, s10, s17
	s_mul_i32 s17, s16, s14
	s_sub_i32 s10, s10, s17
	s_add_i32 s33, s16, 1
	s_sub_i32 s17, s10, s14
	s_cmp_ge_u32 s10, s14
	s_cselect_b32 s16, s33, s16
	s_cselect_b32 s10, s17, s10
	s_add_i32 s17, s16, 1
	s_cmp_ge_u32 s10, s14
	s_cselect_b32 s10, s17, s16
	s_xor_b32 s10, s10, s15
	s_sub_i32 s10, s10, s15
	s_mul_i32 s13, s10, s13
	s_sub_i32 s11, s11, s13
	s_add_i32 s12, s12, s11
